# mod_unit K-loop rewritten by hand: 16 w_ada loads in flight per batch instead of a serialized load+vmcnt0 per k (same fma order, bit-identical)
# speedup vs baseline: 1.0321x; 1.0161x over previous
.LBB0_671:
	s_or_b64 exec, exec, s[6:7]
	s_mul_hi_i32 s6, s12, 0x2aaaaaab
	s_lshr_b32 s7, s6, 31
	s_ashr_i32 s6, s6, 4
	s_add_i32 s6, s6, s7
	s_waitcnt lgkmcnt(0)
	s_barrier
	s_load_dwordx2 s[10:11], s[4:5], 0x38
	s_mul_i32 s7, s6, 0x60
	s_sub_i32 s7, s12, s7
	v_ashrrev_i32_e32 v42, 6, v37
	s_lshl_b32 s8, s7, 6
	s_ashr_i32 s7, s6, 31
	v_lshlrev_b32_e32 v0, 8, v42
	s_lshl_b64 s[14:15], s[6:7], 10
	v_ashrrev_i32_e32 v1, 31, v0
	v_lshl_add_u64 v[0:1], s[14:15], 0, v[0:1]
	s_waitcnt lgkmcnt(0)
	v_mov_b64_e32 v[2:3], s[10:11]
	v_mad_u64_u32 v[2:3], s[10:11], v0, s35, v[2:3]
	v_and_b32_e32 v36, 63, v37
	v_mad_i32_i24 v3, v1, s35, v3
	s_ashr_i32 s9, s8, 31
	v_lshl_add_u64 v[0:1], s[8:9], 2, v[2:3]
	v_lshlrev_b32_e32 v148, 2, v36
	v_mov_b32_e32 v8, 0
	v_lshl_add_u64 v[38:39], v[0:1], 0, v[148:149]
	v_lshlrev_b32_e32 v43, 10, v42
	s_mov_b64 s[10:11], 0
	v_mov_b32_e32 v9, v8
	v_mov_b32_e32 v16, v8
	v_mov_b32_e32 v17, v8
	v_mov_b32_e32 v24, v8
	v_mov_b32_e32 v25, v8
	v_mov_b32_e32 v32, v8
	v_mov_b32_e32 v33, v8
	v_mov_b32_e32 v44, v8
	s_mov_b64 s[14:15], 0x6000
.LBB0_672:
	v_lshl_add_u64 v[40:41], v[38:39], 0, s[10:11]
	global_load_dword v60, v[40:41], off
	v_lshl_add_u64 v[40:41], v[40:41], 0, s[14:15]
	global_load_dword v61, v[40:41], off
	v_lshl_add_u64 v[40:41], v[40:41], 0, s[14:15]
	global_load_dword v62, v[40:41], off
	v_lshl_add_u64 v[40:41], v[40:41], 0, s[14:15]
	global_load_dword v63, v[40:41], off
	v_lshl_add_u64 v[40:41], v[40:41], 0, s[14:15]
	global_load_dword v64, v[40:41], off
	v_lshl_add_u64 v[40:41], v[40:41], 0, s[14:15]
	global_load_dword v65, v[40:41], off
	v_lshl_add_u64 v[40:41], v[40:41], 0, s[14:15]
	global_load_dword v66, v[40:41], off
	v_lshl_add_u64 v[40:41], v[40:41], 0, s[14:15]
	global_load_dword v67, v[40:41], off
	v_lshl_add_u64 v[40:41], v[40:41], 0, s[14:15]
	global_load_dword v68, v[40:41], off
	v_lshl_add_u64 v[40:41], v[40:41], 0, s[14:15]
	global_load_dword v69, v[40:41], off
	v_lshl_add_u64 v[40:41], v[40:41], 0, s[14:15]
	global_load_dword v70, v[40:41], off
	v_lshl_add_u64 v[40:41], v[40:41], 0, s[14:15]
	global_load_dword v71, v[40:41], off
	v_lshl_add_u64 v[40:41], v[40:41], 0, s[14:15]
	global_load_dword v72, v[40:41], off
	v_lshl_add_u64 v[40:41], v[40:41], 0, s[14:15]
	global_load_dword v73, v[40:41], off
	v_lshl_add_u64 v[40:41], v[40:41], 0, s[14:15]
	global_load_dword v74, v[40:41], off
	v_lshl_add_u64 v[40:41], v[40:41], 0, s[14:15]
	global_load_dword v75, v[40:41], off
	s_add_u32 s10, s10, 0x60000
	s_addc_u32 s11, s11, 0
	ds_read_b128 v[100:103], v43 offset:0
	ds_read_b128 v[104:107], v43 offset:4096
	ds_read_b128 v[108:111], v43 offset:8192
	ds_read_b128 v[112:115], v43 offset:12288
	ds_read_b128 v[116:119], v43 offset:16384
	ds_read_b128 v[120:123], v43 offset:20480
	ds_read_b128 v[124:127], v43 offset:24576
	ds_read_b128 v[128:131], v43 offset:28672
	ds_read_b128 v[132:135], v43 offset:32768
	s_waitcnt vmcnt(12) lgkmcnt(0)
	v_fmac_f32_e32 v8, v60, v100
	v_fmac_f32_e32 v9, v60, v104
	v_fmac_f32_e32 v16, v60, v108
	v_fmac_f32_e32 v17, v60, v112
	v_fmac_f32_e32 v24, v60, v116
	v_fmac_f32_e32 v25, v60, v120
	v_fmac_f32_e32 v32, v60, v124
	v_fmac_f32_e32 v33, v60, v128
	v_fmac_f32_e32 v44, v60, v132
	v_fmac_f32_e32 v8, v61, v101
	v_fmac_f32_e32 v9, v61, v105
	v_fmac_f32_e32 v16, v61, v109
	v_fmac_f32_e32 v17, v61, v113
	v_fmac_f32_e32 v24, v61, v117
	v_fmac_f32_e32 v25, v61, v121
	v_fmac_f32_e32 v32, v61, v125
	v_fmac_f32_e32 v33, v61, v129
	v_fmac_f32_e32 v44, v61, v133
	v_fmac_f32_e32 v8, v62, v102
	v_fmac_f32_e32 v9, v62, v106
	v_fmac_f32_e32 v16, v62, v110
	v_fmac_f32_e32 v17, v62, v114
	v_fmac_f32_e32 v24, v62, v118
	v_fmac_f32_e32 v25, v62, v122
	v_fmac_f32_e32 v32, v62, v126
	v_fmac_f32_e32 v33, v62, v130
	v_fmac_f32_e32 v44, v62, v134
	v_fmac_f32_e32 v8, v63, v103
	v_fmac_f32_e32 v9, v63, v107
	v_fmac_f32_e32 v16, v63, v111
	v_fmac_f32_e32 v17, v63, v115
	v_fmac_f32_e32 v24, v63, v119
	v_fmac_f32_e32 v25, v63, v123
	v_fmac_f32_e32 v32, v63, v127
	v_fmac_f32_e32 v33, v63, v131
	v_fmac_f32_e32 v44, v63, v135
	ds_read_b128 v[100:103], v43 offset:16
	ds_read_b128 v[104:107], v43 offset:4112
	ds_read_b128 v[108:111], v43 offset:8208
	ds_read_b128 v[112:115], v43 offset:12304
	ds_read_b128 v[116:119], v43 offset:16400
	ds_read_b128 v[120:123], v43 offset:20496
	ds_read_b128 v[124:127], v43 offset:24592
	ds_read_b128 v[128:131], v43 offset:28688
	ds_read_b128 v[132:135], v43 offset:32784
	s_waitcnt vmcnt(8) lgkmcnt(0)
	v_fmac_f32_e32 v8, v64, v100
	v_fmac_f32_e32 v9, v64, v104
	v_fmac_f32_e32 v16, v64, v108
	v_fmac_f32_e32 v17, v64, v112
	v_fmac_f32_e32 v24, v64, v116
	v_fmac_f32_e32 v25, v64, v120
	v_fmac_f32_e32 v32, v64, v124
	v_fmac_f32_e32 v33, v64, v128
	v_fmac_f32_e32 v44, v64, v132
	v_fmac_f32_e32 v8, v65, v101
	v_fmac_f32_e32 v9, v65, v105
	v_fmac_f32_e32 v16, v65, v109
	v_fmac_f32_e32 v17, v65, v113
	v_fmac_f32_e32 v24, v65, v117
	v_fmac_f32_e32 v25, v65, v121
	v_fmac_f32_e32 v32, v65, v125
	v_fmac_f32_e32 v33, v65, v129
	v_fmac_f32_e32 v44, v65, v133
	v_fmac_f32_e32 v8, v66, v102
	v_fmac_f32_e32 v9, v66, v106
	v_fmac_f32_e32 v16, v66, v110
	v_fmac_f32_e32 v17, v66, v114
	v_fmac_f32_e32 v24, v66, v118
	v_fmac_f32_e32 v25, v66, v122
	v_fmac_f32_e32 v32, v66, v126
	v_fmac_f32_e32 v33, v66, v130
	v_fmac_f32_e32 v44, v66, v134
	v_fmac_f32_e32 v8, v67, v103
	v_fmac_f32_e32 v9, v67, v107
	v_fmac_f32_e32 v16, v67, v111
	v_fmac_f32_e32 v17, v67, v115
	v_fmac_f32_e32 v24, v67, v119
	v_fmac_f32_e32 v25, v67, v123
	v_fmac_f32_e32 v32, v67, v127
	v_fmac_f32_e32 v33, v67, v131
	v_fmac_f32_e32 v44, v67, v135
	ds_read_b128 v[100:103], v43 offset:32
	ds_read_b128 v[104:107], v43 offset:4128
	ds_read_b128 v[108:111], v43 offset:8224
	ds_read_b128 v[112:115], v43 offset:12320
	ds_read_b128 v[116:119], v43 offset:16416
	ds_read_b128 v[120:123], v43 offset:20512
	ds_read_b128 v[124:127], v43 offset:24608
	ds_read_b128 v[128:131], v43 offset:28704
	ds_read_b128 v[132:135], v43 offset:32800
	s_waitcnt vmcnt(4) lgkmcnt(0)
	v_fmac_f32_e32 v8, v68, v100
	v_fmac_f32_e32 v9, v68, v104
	v_fmac_f32_e32 v16, v68, v108
	v_fmac_f32_e32 v17, v68, v112
	v_fmac_f32_e32 v24, v68, v116
	v_fmac_f32_e32 v25, v68, v120
	v_fmac_f32_e32 v32, v68, v124
	v_fmac_f32_e32 v33, v68, v128
	v_fmac_f32_e32 v44, v68, v132
	v_fmac_f32_e32 v8, v69, v101
	v_fmac_f32_e32 v9, v69, v105
	v_fmac_f32_e32 v16, v69, v109
	v_fmac_f32_e32 v17, v69, v113
	v_fmac_f32_e32 v24, v69, v117
	v_fmac_f32_e32 v25, v69, v121
	v_fmac_f32_e32 v32, v69, v125
	v_fmac_f32_e32 v33, v69, v129
	v_fmac_f32_e32 v44, v69, v133
	v_fmac_f32_e32 v8, v70, v102
	v_fmac_f32_e32 v9, v70, v106
	v_fmac_f32_e32 v16, v70, v110
	v_fmac_f32_e32 v17, v70, v114
	v_fmac_f32_e32 v24, v70, v118
	v_fmac_f32_e32 v25, v70, v122
	v_fmac_f32_e32 v32, v70, v126
	v_fmac_f32_e32 v33, v70, v130
	v_fmac_f32_e32 v44, v70, v134
	v_fmac_f32_e32 v8, v71, v103
	v_fmac_f32_e32 v9, v71, v107
	v_fmac_f32_e32 v16, v71, v111
	v_fmac_f32_e32 v17, v71, v115
	v_fmac_f32_e32 v24, v71, v119
	v_fmac_f32_e32 v25, v71, v123
	v_fmac_f32_e32 v32, v71, v127
	v_fmac_f32_e32 v33, v71, v131
	v_fmac_f32_e32 v44, v71, v135
	ds_read_b128 v[100:103], v43 offset:48
	ds_read_b128 v[104:107], v43 offset:4144
	ds_read_b128 v[108:111], v43 offset:8240
	ds_read_b128 v[112:115], v43 offset:12336
	ds_read_b128 v[116:119], v43 offset:16432
	ds_read_b128 v[120:123], v43 offset:20528
	ds_read_b128 v[124:127], v43 offset:24624
	ds_read_b128 v[128:131], v43 offset:28720
	ds_read_b128 v[132:135], v43 offset:32816
	s_waitcnt vmcnt(0) lgkmcnt(0)
	v_fmac_f32_e32 v8, v72, v100
	v_fmac_f32_e32 v9, v72, v104
	v_fmac_f32_e32 v16, v72, v108
	v_fmac_f32_e32 v17, v72, v112
	v_fmac_f32_e32 v24, v72, v116
	v_fmac_f32_e32 v25, v72, v120
	v_fmac_f32_e32 v32, v72, v124
	v_fmac_f32_e32 v33, v72, v128
	v_fmac_f32_e32 v44, v72, v132
	v_fmac_f32_e32 v8, v73, v101
	v_fmac_f32_e32 v9, v73, v105
	v_fmac_f32_e32 v16, v73, v109
	v_fmac_f32_e32 v17, v73, v113
	v_fmac_f32_e32 v24, v73, v117
	v_fmac_f32_e32 v25, v73, v121
	v_fmac_f32_e32 v32, v73, v125
	v_fmac_f32_e32 v33, v73, v129
	v_fmac_f32_e32 v44, v73, v133
	v_fmac_f32_e32 v8, v74, v102
	v_fmac_f32_e32 v9, v74, v106
	v_fmac_f32_e32 v16, v74, v110
	v_fmac_f32_e32 v17, v74, v114
	v_fmac_f32_e32 v24, v74, v118
	v_fmac_f32_e32 v25, v74, v122
	v_fmac_f32_e32 v32, v74, v126
	v_fmac_f32_e32 v33, v74, v130
	v_fmac_f32_e32 v44, v74, v134
	v_fmac_f32_e32 v8, v75, v103
	v_fmac_f32_e32 v9, v75, v107
	v_fmac_f32_e32 v16, v75, v111
	v_fmac_f32_e32 v17, v75, v115
	v_fmac_f32_e32 v24, v75, v119
	v_fmac_f32_e32 v25, v75, v123
	v_fmac_f32_e32 v32, v75, v127
	v_fmac_f32_e32 v33, v75, v131
	v_fmac_f32_e32 v44, v75, v135
	v_add_u32_e32 v43, 64, v43
	s_cmp_eq_u32 s10, 0x600000
	s_cbranch_scc0 .LBB0_672
	s_movk_i32 s7, 0x900
	v_lshlrev_b32_e32 v148, 2, v36
	v_mul_lo_u32 v0, v42, s7
	s_movk_i32 s7, 0x240
	v_or_b32_e32 v0, v148, v0
	v_cmp_gt_i32_e32 vcc, s7, v37
	ds_write2st64_b32 v0, v8, v9 offset0:144 offset1:145
	ds_write2st64_b32 v0, v16, v17 offset0:146 offset1:147
	ds_write2st64_b32 v0, v24, v25 offset0:148 offset1:149
	ds_write2st64_b32 v0, v32, v33 offset0:150 offset1:151
	ds_write_b32 v0, v44 offset:38912
	s_waitcnt lgkmcnt(0)
	s_barrier
	s_and_saveexec_b64 s[10:11], vcc
	s_cbranch_execz .LBB0_663
	s_load_dwordx2 s[14:15], s[4:5], 0x120
	s_lshl_b64 s[16:17], s[8:9], 2
	s_load_dwordx2 s[4:5], s[4:5], 0x40
	s_mul_i32 s7, s6, 0x1800
	v_mov_b32_e32 v4, 0x9000
	s_waitcnt lgkmcnt(0)
	s_add_u32 s14, s14, s16
	s_addc_u32 s15, s15, s17
	s_add_i32 s7, s7, s8
	v_or_b32_e32 v0, s7, v36
	v_ashrrev_i32_e32 v1, 31, v0
	s_mul_i32 s6, s6, 9
	v_lshl_add_u64 v[0:1], v[0:1], 2, s[4:5]
	v_lshl_add_u64 v[2:3], s[14:15], 0, v[148:149]
	v_lshl_add_u32 v4, v37, 2, v4
	s_mov_b64 s[4:5], 0
